# hosted conversion stores write-through (sc0 sc1) so they do not displace the K/V tile images in L2
# speedup vs baseline: 1.0064x; 1.0034x over previous
.Lcjh_n4_0:
	s_cmp_eq_u32 s95, 5
	s_cbranch_scc0 .Lcjh_n5_0
	global_store_dwordx4 v222, v[224:227], s[100:101] sc0 sc1
	v_add_u32_e32 v222, s94, v222
	global_store_dwordx4 v222, v[228:231], s[100:101] sc0 sc1
	v_add_u32_e32 v222, s94, v222
	s_mov_b32 s90, 2
	s_mov_b32 s95, 6
	s_branch .Lcjh_done_0
.Lcjh_n5_0:
	global_store_dwordx4 v222, v[232:235], s[100:101] sc0 sc1
	v_add_u32_e32 v222, s94, v222
	global_store_dwordx4 v222, v[236:239], s[100:101] sc0 sc1
	v_add_u32_e32 v222, s94, v222
	s_mov_b32 s90, 2
	s_mov_b32 s95, 0
